# MLA loop-edge edit: next-tile pointer increments moved from before the loop barrier into the mandatory MFMA->VALU wait slot after the last QK MFMAs
# speedup vs baseline: 1.0024x; 1.0024x over previous
; #define PIN() do { asm volatile("" ::: "memory"); __builtin_amdgcn_sched_barrier(0); } while (0)
; #define MFMA(a, b, c) __builtin_amdgcn_mfma_f32_32x32x16_bf16((a), (b), (c), 0, 0, 0)
; DI unsigned pk2(float a, float b) { f32x2_t v = {a, b}; bf16x2_t r = __builtin_convertvector(v, bf16x2_t); return __builtin_bit_cast(unsigned, r); }
; #define VLD(dst_, s4_) do { _Pragma("unroll") for (int db = 0; db < 4; ++db) dst_[db].v = *(const bf16x8*)(vbase + db * 32 * VSTR + (s4_) * 32); } while (0)
; template <int DQK, int NM>
; DI void attn_item(const bf16_t* Qb, const bf16_t* Kb, size_t mstride, const bf16_t* VTb,
;                   int q0, int nkt, float cs, bf16_t* Orow  , float lam, float outscale, const float* subw, char* smem) {
;     ...
;     {
;       const f32x2_t cs2 = {cs, cs}, mc2 = {mrun * cs, mrun * cs};
;       f32x2_t ps2 = {0.f, 0.f};
; #pragma unroll
;       for (int kb = 0; kb < 2; ++kb)
; #pragma unroll
;         for (int i = 0; i < 16; i += 2) {
;           f32x2_t t = {sacc[kb][i], sacc[kb][i + 1]};
;           t = t * cs2 - mc2;
;           t.x = __builtin_amdgcn_exp2f(t.x); t.y = __builtin_amdgcn_exp2f(t.y);
;           sacc[kb][i] = t.x; sacc[kb][i + 1] = t.y;
;           ps2 = ps2 + t;
;         }
;       lrun += ps2.x + ps2.y;
;     }
;     const char* vbase = cur + KT_BYTES + l31 * VSTR + hh * 16;
;     {
;       struct VF { bf16x8 v; };
;       VF vfa[4], vfb[4];
;     ...
;       VLD(vfa, 0);
; #pragma unroll
;       for (int s4 = 0; s4 < 4; ++s4) {
;         const int kb = s4 >> 1, sp = s4 & 1;
;         PIN();
;         if (s4 < 3) { if (s4 & 1) VLD(vfa, s4 + 1); else VLD(vfb, s4 + 1); }
;         union { bf16x8 v; unsigned u[4]; } pf;
; #pragma unroll
;         for (int e = 0; e < 4; ++e) pf.u[e] = pk2(sacc[kb][8 * sp + 2 * e], sacc[kb][8 * sp + 2 * e + 1]);
;         PIN();
; #pragma unroll
;         for (int db = 0; db < 4; ++db) { if (s4 & 1) oacc[db] = MFMA(vfb[db].v, pf.v, oacc[db]); else oacc[db] = MFMA(vfa[db].v, pf.v, oacc[db]); }
;         {
;           char* b_ = smem + ((kt + 1) & 1) * BUF;
;           if (s4 == 0) { *(uint4*)(b_ + klo[0]) = kreg0; if (NKC > 2) *(uint4*)(b_ + klo[2]) = kreg2; }
;           if (s4 == 1) { *(uint4*)(b_ + klo[1]) = kreg1; }
;           if (s4 == 2) { *(uint4*)(b_ + vlo0) = vreg0; }
;           if (s4 == 3) { *(uint4*)(b_ + vlo1) = vreg1; }
;         }
;       }
;     ...
;     }
;     PIN();
;     __syncthreads();
.LBB0_126:
	v_mul_f32_e32 v196, 0x3dd53b95, v218
	v_fma_f32 v80, v80, s26, -v196
	v_fma_f32 v81, v81, s26, -v196
	v_fma_f32 v64, v64, s26, -v196
	v_fma_f32 v65, v65, s26, -v196
	v_exp_f32_e32 v220, v80
	v_exp_f32_e32 v221, v81
	v_fma_f32 v80, v82, s26, -v196
	v_fma_f32 v81, v83, s26, -v196
	v_fma_f32 v82, v88, s26, -v196
	v_fma_f32 v83, v89, s26, -v196
	v_exp_f32_e32 v222, v80
	v_exp_f32_e32 v223, v81
	v_fma_f32 v80, v84, s26, -v196
	v_fma_f32 v81, v85, s26, -v196
	v_exp_f32_e32 v228, v82
	v_exp_f32_e32 v224, v80
	v_exp_f32_e32 v225, v81
	v_fma_f32 v80, v86, s26, -v196
	v_fma_f32 v81, v87, s26, -v196
	v_exp_f32_e32 v229, v83
	v_exp_f32_e32 v226, v80
	v_exp_f32_e32 v227, v81
	v_fma_f32 v82, v90, s26, -v196
	v_fma_f32 v83, v91, s26, -v196
	v_exp_f32_e32 v230, v82
	v_exp_f32_e32 v231, v83
	v_fma_f32 v82, v92, s26, -v196
	v_fma_f32 v83, v93, s26, -v196
	v_exp_f32_e32 v232, v82
	v_exp_f32_e32 v233, v83
	v_fma_f32 v82, v94, s26, -v196
	v_fma_f32 v83, v95, s26, -v196
	v_exp_f32_e32 v234, v82
	v_exp_f32_e32 v235, v83
	v_exp_f32_e32 v236, v64
	v_exp_f32_e32 v237, v65
	v_fma_f32 v64, v66, s26, -v196
	v_fma_f32 v65, v67, s26, -v196
	v_exp_f32_e32 v238, v64
	v_exp_f32_e32 v239, v65
	v_fma_f32 v64, v68, s26, -v196
	v_fma_f32 v65, v69, s26, -v196
	v_exp_f32_e32 v240, v64
	v_exp_f32_e32 v241, v65
	v_fma_f32 v64, v70, s26, -v196
	v_fma_f32 v65, v71, s26, -v196
	v_exp_f32_e32 v242, v64
	v_exp_f32_e32 v243, v65
	v_fma_f32 v66, v72, s26, -v196
	v_fma_f32 v67, v73, s26, -v196
	v_exp_f32_e32 v244, v66
	v_exp_f32_e32 v245, v67
	v_fma_f32 v66, v74, s26, -v196
	v_fma_f32 v67, v75, s26, -v196
	v_exp_f32_e32 v246, v66
	v_exp_f32_e32 v247, v67
	v_fma_f32 v66, v76, s26, -v196
	v_fma_f32 v67, v77, s26, -v196
	v_exp_f32_e32 v248, v66
	v_exp_f32_e32 v249, v67
	v_fma_f32 v66, v78, s26, -v196
	v_fma_f32 v67, v79, s26, -v196
	v_exp_f32_e32 v250, v66
	v_exp_f32_e32 v251, v67
	v_add3_u32 v219, s25, v214, v170
	s_cmp_eq_u32 s24, 1
	s_cselect_b32 s24, 0xac00, 0
	ds_read_b128 v[64:67], v219 offset:25600
	ds_read_b128 v[68:71], v219 offset:30208
	ds_read_b128 v[72:75], v219 offset:34816
	ds_read_b128 v[76:79], v219 offset:39424
	s_add_i32 s24, s24, 0
	v_add_u32_e32 v206, s24, v197
	v_add_u32_e32 v211, s24, v216
	ds_read_b128 v[80:83], v219 offset:25632
	ds_read_b128 v[84:87], v219 offset:30240
	ds_read_b128 v[88:91], v219 offset:34848
	ds_read_b128 v[92:95], v219 offset:39456
	v_add_f32_e32 v203, v220, v221
	v_add_f32_e32 v203, v222, v203
	v_add_f32_e32 v203, v223, v203
	v_add_f32_e32 v203, v224, v203
	v_add_f32_e32 v203, v225, v203
	v_add_f32_e32 v203, v226, v203
	v_add_f32_e32 v203, v227, v203
	v_cvt_pk_bf16_f32 v220, v220, v221
	v_cvt_pk_bf16_f32 v221, v222, v223
	v_cvt_pk_bf16_f32 v222, v224, v225
	v_cvt_pk_bf16_f32 v223, v226, v227
	s_waitcnt lgkmcnt(7)
	s_nop 0
	v_mfma_f32_32x32x16_bf16 v[32:47], v[64:67], v[220:223], v[32:47]
	v_add_f32_e32 v203, v228, v203
	v_add_f32_e32 v203, v229, v203
	s_waitcnt vmcnt(4)
	ds_write_b128 v206, v[158:161]
	s_waitcnt vmcnt(2)
	ds_write_b128 v211, v[162:165]
	s_waitcnt lgkmcnt(8)
	v_mfma_f32_32x32x16_bf16 v[48:63], v[68:71], v[220:223], v[48:63]
	v_add_f32_e32 v203, v230, v203
	v_add_f32_e32 v203, v231, v203
	s_waitcnt lgkmcnt(7)
	v_mfma_f32_32x32x16_bf16 v[16:31], v[72:75], v[220:223], v[16:31]
	v_add_f32_e32 v203, v232, v203
	v_add_f32_e32 v203, v233, v203
	s_waitcnt lgkmcnt(6)
	v_mfma_f32_32x32x16_bf16 v[0:15], v[76:79], v[220:223], v[0:15]
	v_add_f32_e32 v203, v234, v203
	v_add_f32_e32 v203, v235, v203
	ds_read_b128 v[64:67], v219 offset:25664
	ds_read_b128 v[68:71], v219 offset:30272
	ds_read_b128 v[72:75], v219 offset:34880
	ds_read_b128 v[76:79], v219 offset:39488
	v_cvt_pk_bf16_f32 v158, v228, v229
	v_cvt_pk_bf16_f32 v159, v230, v231
	v_cvt_pk_bf16_f32 v160, v232, v233
	v_cvt_pk_bf16_f32 v161, v234, v235
	s_waitcnt lgkmcnt(9)
	s_nop 0
	v_mfma_f32_32x32x16_bf16 v[32:47], v[80:83], v[158:161], v[32:47]
	v_add_f32_e32 v203, v236, v203
	v_add_f32_e32 v203, v237, v203
	v_add_u32_e32 v80, s24, v215
	ds_write_b128 v80, v[154:157]
	s_waitcnt lgkmcnt(9)
	v_mfma_f32_32x32x16_bf16 v[48:63], v[84:87], v[158:161], v[48:63]
	v_add_f32_e32 v203, v238, v203
	v_add_f32_e32 v203, v239, v203
	s_waitcnt lgkmcnt(8)
	v_mfma_f32_32x32x16_bf16 v[16:31], v[88:91], v[158:161], v[16:31]
	v_add_f32_e32 v203, v240, v203
	v_add_f32_e32 v203, v241, v203
	s_waitcnt lgkmcnt(7)
	v_mfma_f32_32x32x16_bf16 v[0:15], v[92:95], v[158:161], v[0:15]
	v_add_f32_e32 v203, v242, v203
	v_add_f32_e32 v203, v243, v203
	ds_read_b128 v[80:83], v219 offset:25696
	ds_read_b128 v[84:87], v219 offset:30304
	ds_read_b128 v[88:91], v219 offset:34912
	ds_read_b128 v[92:95], v219 offset:39520
	v_cvt_pk_bf16_f32 v154, v236, v237
	v_cvt_pk_bf16_f32 v155, v238, v239
	v_cvt_pk_bf16_f32 v156, v240, v241
	v_cvt_pk_bf16_f32 v157, v242, v243
	s_waitcnt lgkmcnt(8)
	s_nop 0
	v_mfma_f32_32x32x16_bf16 v[32:47], v[64:67], v[154:157], v[32:47]
	v_add_f32_e32 v203, v244, v203
	v_add_f32_e32 v203, v245, v203
	v_add_u32_e32 v64, s24, v182
	s_waitcnt vmcnt(1)
	ds_write_b128 v64, v[150:153] offset:25600
	s_waitcnt lgkmcnt(8)
	v_mfma_f32_32x32x16_bf16 v[48:63], v[68:71], v[154:157], v[48:63]
	v_add_f32_e32 v203, v246, v203
	v_add_f32_e32 v203, v247, v203
	s_waitcnt lgkmcnt(7)
	v_mfma_f32_32x32x16_bf16 v[16:31], v[72:75], v[154:157], v[16:31]
	v_add_f32_e32 v203, v248, v203
	v_add_f32_e32 v203, v249, v203
	s_waitcnt lgkmcnt(6)
	v_mfma_f32_32x32x16_bf16 v[0:15], v[76:79], v[154:157], v[0:15]
	v_add_f32_e32 v203, v250, v203
	v_add_f32_e32 v203, v251, v203
	v_cvt_pk_bf16_f32 v64, v244, v245
	v_cvt_pk_bf16_f32 v65, v246, v247
	v_cvt_pk_bf16_f32 v66, v248, v249
	v_cvt_pk_bf16_f32 v67, v250, v251
	s_waitcnt lgkmcnt(4)
	s_nop 0
	v_mfma_f32_32x32x16_bf16 v[32:47], v[80:83], v[64:67], v[32:47]
	v_add_u32_e32 v68, s24, v184
	s_waitcnt vmcnt(0)
	ds_write_b128 v68, v[146:149] offset:25600
	v_add_f32_e32 v185, v185, v203
	s_waitcnt lgkmcnt(4)
	v_mfma_f32_32x32x16_bf16 v[48:63], v[84:87], v[64:67], v[48:63]
	s_waitcnt lgkmcnt(3)
	v_mfma_f32_32x32x16_bf16 v[16:31], v[88:91], v[64:67], v[16:31]
	s_waitcnt lgkmcnt(2)
	v_mfma_f32_32x32x16_bf16 v[0:15], v[92:95], v[64:67], v[0:15]
	s_cmpk_eq_i32 s37, 0x84
	s_waitcnt lgkmcnt(0)
	s_barrier
	s_cbranch_scc1 .LBB0_129
; #define PIN() do { asm volatile("" ::: "memory"); __builtin_amdgcn_sched_barrier(0); } while (0)
; #define GLOAD(kt_) do { const bf16_t* kp_ = Kb + (size_t)(kt_) * 64 * DQK; const bf16_t* vp_ = VTb + (kt_) * 64; \
;     kreg0 = *(const uint4*)(kp_ + kgo[0]); kreg1 = *(const uint4*)(kp_ + kgo[1]); if (NKC > 2) kreg2 = *(const uint4*)(kp_ + kgo[2]); \
;     vreg0 = *(const uint4*)(vp_ + vgo0); vreg1 = *(const uint4*)(vp_ + vgo1); } while (0)
; #define SSTORE(buf_) do { char* b_ = (buf_); \
;     *(uint4*)(b_ + klo[0]) = kreg0; *(uint4*)(b_ + klo[1]) = kreg1; if (NKC > 2) *(uint4*)(b_ + klo[2]) = kreg2; \
;     *(uint4*)(b_ + vlo0) = vreg0; *(uint4*)(b_ + vlo1) = vreg1; } while (0)
; #define KLD(dst_, s_) do { dst_[0] = *(const bf16x8*)(kbase + (s_) * 32); dst_[1] = *(const bf16x8*)(kbase + 32 * KSTR + (s_) * 32); \
;         dst_[2] = *(const bf16x8*)(kbase + ((s_) + 1) * 32); dst_[3] = *(const bf16x8*)(kbase + 32 * KSTR + ((s_) + 1) * 32); } while (0)
; template <int DQK, int NM>
; DI void attn_item(const bf16_t* Qb, const bf16_t* Kb, size_t mstride, const bf16_t* VTb,
;                   int q0, int nkt, float cs, bf16_t* Orow  , float lam, float outscale, const float* subw, char* smem) {
;     ...
;   GLOAD(0); SSTORE(smem); __syncthreads();
;   for (int kt = 0; kt < nkt; ++kt) {
;     const char* cur = smem + (kt & 1) * BUF;
;     GLOAD(kt + 1 < nkt ? kt + 1 : kt);
;     PIN();
;     f32x16 sacc[2];
; #pragma unroll
;     for (int kb = 0; kb < 2; ++kb)
; #pragma unroll
;       for (int i = 0; i < 16; ++i) sacc[kb][i] = 0.f;
;     const char* kbase = cur + (m * 64 + l31) * KSTR + hh * 16;
;     {
;       bf16x8 kfa[4], kfb[4];
;     ...
;       KLD(kfa, 0);
; #pragma unroll
;       for (int g = 0; g < NS / 2; ++g) {
;         PIN();
;         if (g + 1 < NS / 2) { if (g & 1) KLD(kfa, 2 * g + 2); else KLD(kfb, 2 * g + 2); }
;         PIN();
;         if (g & 1) KMM(kfb, 2 * g); else KMM(kfa, 2 * g);
;       }
;     ...
;     }
;     float mx = sacc[0][0];
; #pragma unroll
;     for (int i = 1; i < 16; ++i) mx = fmaxf(mx, sacc[0][i]);
; #pragma unroll
;     for (int i = 0; i < 16; ++i) mx = fmaxf(mx, sacc[1][i]);
;     {
;       const auto rr = __builtin_amdgcn_permlane32_swap(__float_as_uint(mx), __float_as_uint(mx), false, false);
;       mx = fmaxf(__uint_as_float(rr[0]), __uint_as_float(rr[1]));
;     }
.LBB0_127:
	v_lshl_add_u64 v[64:65], s[20:21], 0, v[190:191]
	v_lshl_add_u64 v[66:67], s[20:21], 0, v[192:193]
	global_load_dwordx4 v[158:161], v[64:65], off
	global_load_dwordx4 v[154:157], v[66:67], off
	v_lshl_add_u64 v[64:65], s[20:21], 0, v[194:195]
	s_mov_b32 s24, 0xca06000
	v_add_co_u32_e32 v64, vcc, s24, v64
	v_lshl_add_u64 v[66:67], s[20:21], 0, v[186:187]
	s_nop 0
	v_addc_co_u32_e32 v65, vcc, 0, v65, vcc
	global_load_dwordx4 v[162:165], v[64:65], off
	global_load_dwordx4 v[150:153], v[66:67], off
	v_lshl_add_u64 v[64:65], s[20:21], 0, v[188:189]
	global_load_dwordx4 v[146:149], v[64:65], off
	s_and_b32 s24, 1, s37
	s_cselect_b32 s25, 0, 0xac00
	s_add_i32 s25, s25, 0
	v_add3_u32 v196, s25, v217, v170
	ds_read_b128 v[64:67], v196
	ds_read_b128 v[220:223], v196 offset:32
	ds_read_b128 v[68:71], v196 offset:12800
	ds_read_b128 v[224:227], v196 offset:12832
	ds_read_b128 v[228:231], v196 offset:64
	ds_read_b128 v[232:235], v196 offset:96
	ds_read_b128 v[236:239], v196 offset:12864
	ds_read_b128 v[240:243], v196 offset:12896
	s_waitcnt lgkmcnt(7)
	v_mfma_f32_32x32x16_bf16 v[80:95], v[64:67], v[142:145], 0
	s_waitcnt lgkmcnt(5)
	v_mfma_f32_32x32x16_bf16 v[64:79], v[68:71], v[142:145], 0
	v_mfma_f32_32x32x16_bf16 v[80:95], v[220:223], v[136:139], v[80:95]
	s_waitcnt lgkmcnt(4)
	v_mfma_f32_32x32x16_bf16 v[64:79], v[224:227], v[136:139], v[64:79]
	ds_read_b128 v[220:223], v196 offset:128
	ds_read_b128 v[224:227], v196 offset:160
	ds_read_b128 v[244:247], v196 offset:12928
	ds_read_b128 v[248:251], v196 offset:12960
	s_waitcnt lgkmcnt(7)
	v_mfma_f32_32x32x16_bf16 v[80:95], v[228:231], v[132:135], v[80:95]
	s_waitcnt lgkmcnt(5)
	v_mfma_f32_32x32x16_bf16 v[64:79], v[236:239], v[132:135], v[64:79]
	v_mfma_f32_32x32x16_bf16 v[80:95], v[232:235], v[128:131], v[80:95]
	s_waitcnt lgkmcnt(4)
	v_mfma_f32_32x32x16_bf16 v[64:79], v[240:243], v[128:131], v[64:79]
	ds_read_b128 v[228:231], v196 offset:192
	ds_read_b128 v[232:235], v196 offset:224
	ds_read_b128 v[236:239], v196 offset:12992
	ds_read_b128 v[240:243], v196 offset:13024
	s_waitcnt lgkmcnt(7)
	v_mfma_f32_32x32x16_bf16 v[80:95], v[220:223], v[124:127], v[80:95]
	s_waitcnt lgkmcnt(5)
	v_mfma_f32_32x32x16_bf16 v[64:79], v[244:247], v[124:127], v[64:79]
	v_mfma_f32_32x32x16_bf16 v[80:95], v[224:227], v[120:123], v[80:95]
	s_waitcnt lgkmcnt(4)
	v_mfma_f32_32x32x16_bf16 v[64:79], v[248:251], v[120:123], v[64:79]
	ds_read_b128 v[220:223], v196 offset:256
	ds_read_b128 v[224:227], v196 offset:288
	ds_read_b128 v[244:247], v196 offset:13056
	ds_read_b128 v[248:251], v196 offset:13088
	s_waitcnt lgkmcnt(7)
	v_mfma_f32_32x32x16_bf16 v[80:95], v[228:231], v[116:119], v[80:95]
	s_waitcnt lgkmcnt(5)
	v_mfma_f32_32x32x16_bf16 v[64:79], v[236:239], v[116:119], v[64:79]
	v_mfma_f32_32x32x16_bf16 v[80:95], v[232:235], v[112:115], v[80:95]
	s_waitcnt lgkmcnt(4)
	v_mfma_f32_32x32x16_bf16 v[64:79], v[240:243], v[112:115], v[64:79]
	ds_read_b128 v[228:231], v196 offset:320
	ds_read_b128 v[232:235], v196 offset:352
	ds_read_b128 v[236:239], v196 offset:13120
	ds_read_b128 v[240:243], v196 offset:13152
	s_waitcnt lgkmcnt(7)
	v_mfma_f32_32x32x16_bf16 v[80:95], v[220:223], v[108:111], v[80:95]
	s_waitcnt lgkmcnt(5)
	v_mfma_f32_32x32x16_bf16 v[64:79], v[244:247], v[108:111], v[64:79]
	v_mfma_f32_32x32x16_bf16 v[80:95], v[224:227], v[104:107], v[80:95]
	s_waitcnt lgkmcnt(4)
	v_mfma_f32_32x32x16_bf16 v[64:79], v[248:251], v[104:107], v[64:79]
	s_waitcnt lgkmcnt(3)
	v_mfma_f32_32x32x16_bf16 v[80:95], v[228:231], v[100:103], v[80:95]
	s_waitcnt lgkmcnt(2)
	v_mfma_f32_32x32x16_bf16 v[80:95], v[232:235], v[96:99], v[80:95]
	s_waitcnt lgkmcnt(1)
	v_mfma_f32_32x32x16_bf16 v[64:79], v[236:239], v[100:103], v[64:79]
	s_mov_b64 s[34:35], 0x80
	s_add_i32 s37, s37, 1
	v_lshl_add_u64 v[186:187], v[186:187], 0, s[34:35]
	v_lshl_add_u64 v[188:189], v[188:189], 0, s[34:35]
	s_mov_b64 s[34:35], 0x6000
	v_lshl_add_u64 v[190:191], v[190:191], 0, s[34:35]
	v_lshl_add_u64 v[192:193], v[192:193], 0, s[34:35]
	v_lshl_add_u64 v[194:195], v[194:195], 0, s[34:35]
	s_nop 1
	v_max_f32_e32 v196, v81, v81
	v_max_f32_e32 v219, v80, v80
	v_max_f32_e32 v196, v219, v196
	v_max3_f32 v196, v196, v82, v83
	v_max3_f32 v196, v196, v84, v85
	v_max3_f32 v196, v196, v86, v87
	v_max3_f32 v196, v196, v88, v89
	s_waitcnt lgkmcnt(0)
	v_mfma_f32_32x32x16_bf16 v[64:79], v[240:243], v[96:99], v[64:79]
	v_max3_f32 v196, v196, v90, v91
	v_max3_f32 v196, v196, v92, v93
	v_max3_f32 v196, v196, v94, v95
	s_nop 8
	v_max3_f32 v196, v196, v64, v65
	v_max3_f32 v196, v196, v66, v67
	v_max3_f32 v196, v196, v68, v69
	v_max3_f32 v196, v196, v70, v71
	v_max3_f32 v196, v196, v72, v73
	v_max3_f32 v196, v196, v74, v75
	v_max3_f32 v196, v196, v76, v77
	v_max3_f32 v196, v196, v78, v79
	v_mov_b32_e32 v219, v196
	s_nop 1
	v_permlane32_swap_b32_e32 v196, v219
	v_max_f32_e32 v219, v219, v219
	v_max_f32_e32 v196, v196, v196
	v_max_f32_e32 v196, v196, v219
	v_sub_f32_e32 v219, v196, v218
	v_mul_f32_e32 v219, 0x3dd53b95, v219
	v_cmp_lt_f32_e32 vcc, s5, v219
	s_cbranch_vccz .LBB0_126
; template <int DQK, int NM>
; DI void attn_item(const bf16_t* Qb, const bf16_t* Kb, size_t mstride, const bf16_t* VTb,
;                   int q0, int nkt, float cs, bf16_t* Orow  , float lam, float outscale, const float* subw, char* smem) {
;     ...
;     if (__any((mx - mrun) * cs > 8.f)) {
;       const float mnew = fmaxf(mrun, mx);
;       const float alpha = __builtin_amdgcn_exp2f((mrun - mnew) * cs);
;       mrun = mnew;
;       lrun *= alpha;
; #pragma unroll
;       for (int db = 0; db < 4; ++db)
; #pragma unroll
;         for (int i = 0; i < 16; ++i) oacc[db][i] *= alpha;
;     }
	v_max_f32_e32 v196, v196, v196
	v_max_f32_e32 v219, v218, v218
	v_max_f32_e32 v219, v219, v196
	v_sub_f32_e32 v196, v218, v219
	v_mul_f32_e32 v196, 0x3dd53b95, v196
	v_exp_f32_e32 v196, v196
	v_mov_b32_e32 v218, v219
	v_pk_mul_f32 v[46:47], v[46:47], v[196:197] op_sel_hi:[1,0]
	v_pk_mul_f32 v[44:45], v[44:45], v[196:197] op_sel_hi:[1,0]
	v_pk_mul_f32 v[42:43], v[42:43], v[196:197] op_sel_hi:[1,0]
	v_pk_mul_f32 v[40:41], v[40:41], v[196:197] op_sel_hi:[1,0]
	v_pk_mul_f32 v[38:39], v[38:39], v[196:197] op_sel_hi:[1,0]
	v_pk_mul_f32 v[36:37], v[36:37], v[196:197] op_sel_hi:[1,0]
	v_pk_mul_f32 v[34:35], v[34:35], v[196:197] op_sel_hi:[1,0]
	v_pk_mul_f32 v[32:33], v[32:33], v[196:197] op_sel_hi:[1,0]
	v_pk_mul_f32 v[62:63], v[62:63], v[196:197] op_sel_hi:[1,0]
	v_pk_mul_f32 v[60:61], v[60:61], v[196:197] op_sel_hi:[1,0]
	v_pk_mul_f32 v[58:59], v[58:59], v[196:197] op_sel_hi:[1,0]
	v_pk_mul_f32 v[56:57], v[56:57], v[196:197] op_sel_hi:[1,0]
	v_pk_mul_f32 v[54:55], v[54:55], v[196:197] op_sel_hi:[1,0]
	v_pk_mul_f32 v[52:53], v[52:53], v[196:197] op_sel_hi:[1,0]
	v_pk_mul_f32 v[50:51], v[50:51], v[196:197] op_sel_hi:[1,0]
	v_pk_mul_f32 v[48:49], v[48:49], v[196:197] op_sel_hi:[1,0]
	v_pk_mul_f32 v[30:31], v[30:31], v[196:197] op_sel_hi:[1,0]
	v_pk_mul_f32 v[28:29], v[28:29], v[196:197] op_sel_hi:[1,0]
	v_pk_mul_f32 v[26:27], v[26:27], v[196:197] op_sel_hi:[1,0]
	v_pk_mul_f32 v[24:25], v[24:25], v[196:197] op_sel_hi:[1,0]
	v_pk_mul_f32 v[22:23], v[22:23], v[196:197] op_sel_hi:[1,0]
	v_pk_mul_f32 v[20:21], v[20:21], v[196:197] op_sel_hi:[1,0]
	v_pk_mul_f32 v[18:19], v[18:19], v[196:197] op_sel_hi:[1,0]
	v_pk_mul_f32 v[16:17], v[16:17], v[196:197] op_sel_hi:[1,0]
	v_pk_mul_f32 v[14:15], v[14:15], v[196:197] op_sel_hi:[1,0]
	v_pk_mul_f32 v[12:13], v[12:13], v[196:197] op_sel_hi:[1,0]
	v_pk_mul_f32 v[10:11], v[10:11], v[196:197] op_sel_hi:[1,0]
	v_pk_mul_f32 v[8:9], v[8:9], v[196:197] op_sel_hi:[1,0]
	v_pk_mul_f32 v[6:7], v[6:7], v[196:197] op_sel_hi:[1,0]
	v_pk_mul_f32 v[4:5], v[4:5], v[196:197] op_sel_hi:[1,0]
	v_pk_mul_f32 v[2:3], v[2:3], v[196:197] op_sel_hi:[1,0]
	v_pk_mul_f32 v[0:1], v[0:1], v[196:197] op_sel_hi:[1,0]
	v_mul_f32_e32 v185, v185, v196
	s_branch .LBB0_126
